# MLA fast path: K_A fragments all requested up front (borrowing dead S_B registers), early V_B fragments, slot-availability driven LDS prefetch
# baseline (speedup 1.0000x reference)
.Lmla_fast_l0:
	s_mul_i32 s1, s18, 0xa800
	v_add3_u32 v14, s1, v148, v191
	v_add_u32_e32 v0, s1, v183
	v_add3_u32 v0, v0, v184, v185
	ds_read_b128 v[2:5], v14 offset:0
	ds_read_b128 v[6:9], v14 offset:32
	ds_read_b128 v[10:13], v14 offset:64
	ds_read_b128 v[140:143], v14 offset:96
	ds_read_b128 v[234:237], v14 offset:128
	ds_read_b128 v[240:243], v14 offset:160
	ds_read_b128 v[202:205], v14 offset:6656
	ds_read_b128 v[206:209], v14 offset:6688
	ds_read_b128 v[210:213], v14 offset:6720
	ds_read_b128 v[214:217], v14 offset:6752
	ds_read_b128 v[218:221], v14 offset:6784
	ds_read_b128 v[222:225], v14 offset:6816
	s_cmp_lg_u32 s98, 0
	s_cbranch_scc1 .Lmla_l0_negm_ok
	v_xor_b32_e32 v124, 0x80000000, v201
	v_xor_b32_e32 v125, 0x80000000, v201
	v_xor_b32_e32 v126, 0x80000000, v201
	v_xor_b32_e32 v127, 0x80000000, v201
	v_xor_b32_e32 v128, 0x80000000, v201
	v_xor_b32_e32 v129, 0x80000000, v201
	v_xor_b32_e32 v130, 0x80000000, v201
	v_xor_b32_e32 v131, 0x80000000, v201
	v_xor_b32_e32 v132, 0x80000000, v201
	v_xor_b32_e32 v133, 0x80000000, v201
	v_xor_b32_e32 v134, 0x80000000, v201
	v_xor_b32_e32 v135, 0x80000000, v201
	v_xor_b32_e32 v136, 0x80000000, v201
	v_xor_b32_e32 v137, 0x80000000, v201
	v_xor_b32_e32 v138, 0x80000000, v201
	v_xor_b32_e32 v139, 0x80000000, v201
	s_mov_b32 s98, 1
.Lmla_l0_negm_ok:
	s_nop 1
	s_waitcnt lgkmcnt(11)
	v_mfma_f32_32x32x16_bf16 v[64:79], v[2:5], v[92:95], v[124:139]
	ds_read_b128 v[2:5], v14 offset:21504
	s_waitcnt lgkmcnt(11)
	v_mfma_f32_32x32x16_bf16 v[64:79], v[6:9], v[96:99], v[64:79]
	ds_read_b128 v[6:9], v14 offset:21536
	s_waitcnt lgkmcnt(11)
	v_mfma_f32_32x32x16_bf16 v[64:79], v[10:13], v[100:103], v[64:79]
	ds_read_b128 v[10:13], v14 offset:21568
	s_waitcnt lgkmcnt(11)
	v_mfma_f32_32x32x16_bf16 v[64:79], v[140:143], v[104:107], v[64:79]
	ds_read_b128 v[140:143], v14 offset:21600
	s_waitcnt lgkmcnt(11)
	v_mfma_f32_32x32x16_bf16 v[64:79], v[234:237], v[116:119], v[64:79]
	ds_read_b128 v[234:237], v14 offset:21632
	s_waitcnt lgkmcnt(11)
	v_mfma_f32_32x32x16_bf16 v[64:79], v[240:243], v[120:123], v[64:79]
	ds_read_b128 v[240:243], v14 offset:21664
	s_waitcnt lgkmcnt(11)
	v_mfma_f32_32x32x16_bf16 v[48:63], v[202:205], v[92:95], v[124:139]
	s_waitcnt lgkmcnt(10)
	v_mfma_f32_32x32x16_bf16 v[48:63], v[206:209], v[96:99], v[48:63]
	s_waitcnt lgkmcnt(9)
	v_mfma_f32_32x32x16_bf16 v[48:63], v[210:213], v[100:103], v[48:63]
	s_waitcnt lgkmcnt(8)
	v_mfma_f32_32x32x16_bf16 v[48:63], v[214:217], v[104:107], v[48:63]
	s_waitcnt lgkmcnt(7)
	v_mfma_f32_32x32x16_bf16 v[48:63], v[218:221], v[116:119], v[48:63]
	s_waitcnt lgkmcnt(6)
	v_mfma_f32_32x32x16_bf16 v[48:63], v[222:225], v[120:123], v[48:63]
	v_exp_f32_e32 v64, v64
	v_exp_f32_e32 v65, v65
	s_waitcnt lgkmcnt(5)
	v_mfma_f32_32x32x16_bf16 v[202:217], v[2:5], v[92:95], v[124:139]
	ds_read_b128 v[2:5], v14 offset:28160
	v_exp_f32_e32 v66, v66
	v_exp_f32_e32 v67, v67
	v_exp_f32_e32 v68, v68
	v_exp_f32_e32 v69, v69
	v_exp_f32_e32 v70, v70
	s_waitcnt lgkmcnt(5)
	v_mfma_f32_32x32x16_bf16 v[202:217], v[6:9], v[96:99], v[202:217]
	ds_read_b128 v[6:9], v14 offset:28192
	v_exp_f32_e32 v71, v71
	v_pk_add_f32 v[246:247], v[64:65], v[66:67]
	v_exp_f32_e32 v72, v72
	v_exp_f32_e32 v73, v73
	v_exp_f32_e32 v74, v74
	s_waitcnt lgkmcnt(5)
	v_mfma_f32_32x32x16_bf16 v[202:217], v[10:13], v[100:103], v[202:217]
	ds_read_b128 v[10:13], v14 offset:28224
	v_exp_f32_e32 v75, v75
	v_pk_add_f32 v[248:249], v[68:69], v[70:71]
	v_exp_f32_e32 v76, v76
	v_exp_f32_e32 v77, v77
	v_pk_add_f32 v[246:247], v[246:247], v[72:73]
	s_waitcnt lgkmcnt(5)
	v_mfma_f32_32x32x16_bf16 v[202:217], v[140:143], v[104:107], v[202:217]
	ds_read_b128 v[140:143], v14 offset:28256
	v_exp_f32_e32 v78, v78
	v_exp_f32_e32 v79, v79
	v_pk_add_f32 v[248:249], v[248:249], v[74:75]
	v_exp_f32_e32 v48, v48
	v_exp_f32_e32 v49, v49
	s_waitcnt lgkmcnt(5)
	v_mfma_f32_32x32x16_bf16 v[202:217], v[234:237], v[116:119], v[202:217]
	ds_read_b128 v[234:237], v14 offset:28288
	v_pk_add_f32 v[246:247], v[246:247], v[76:77]
	v_exp_f32_e32 v50, v50
	v_exp_f32_e32 v51, v51
	v_pk_add_f32 v[248:249], v[248:249], v[78:79]
	v_exp_f32_e32 v52, v52
	s_waitcnt lgkmcnt(5)
	v_mfma_f32_32x32x16_bf16 v[202:217], v[240:243], v[120:123], v[202:217]
	ds_read_b128 v[240:243], v14 offset:28320
	v_exp_f32_e32 v53, v53
	v_pk_add_f32 v[246:247], v[246:247], v[48:49]
	v_exp_f32_e32 v54, v54
	v_exp_f32_e32 v55, v55
	v_pk_add_f32 v[248:249], v[248:249], v[50:51]
	s_waitcnt lgkmcnt(5)
	v_mfma_f32_32x32x16_bf16 v[218:233], v[2:5], v[92:95], v[124:139]
	ds_read_b64_tr_b16 v[2:3], v0 offset:13312
	ds_read_b64_tr_b16 v[4:5], v0 offset:13824
	v_exp_f32_e32 v56, v56
	v_exp_f32_e32 v57, v57
	v_pk_add_f32 v[246:247], v[246:247], v[52:53]
	v_exp_f32_e32 v58, v58
	v_exp_f32_e32 v59, v59
	s_waitcnt lgkmcnt(6)
	v_mfma_f32_32x32x16_bf16 v[218:233], v[6:9], v[96:99], v[218:233]
	ds_read_b64_tr_b16 v[6:7], v0 offset:17408
	ds_read_b64_tr_b16 v[8:9], v0 offset:17920
	v_pk_add_f32 v[248:249], v[248:249], v[54:55]
	v_exp_f32_e32 v60, v60
	v_exp_f32_e32 v61, v61
	v_pk_add_f32 v[246:247], v[246:247], v[56:57]
	v_exp_f32_e32 v62, v62
	s_waitcnt lgkmcnt(7)
	v_mfma_f32_32x32x16_bf16 v[218:233], v[10:13], v[100:103], v[218:233]
	ds_read_b64_tr_b16 v[10:11], v0 offset:14336
	ds_read_b64_tr_b16 v[12:13], v0 offset:14848
	v_exp_f32_e32 v63, v63
	v_pk_add_f32 v[248:249], v[248:249], v[58:59]
	v_pk_add_f32 v[246:247], v[246:247], v[60:61]
	v_pk_add_f32 v[248:249], v[248:249], v[62:63]
	v_pk_add_f32 v[246:247], v[246:247], v[248:249]
	s_waitcnt lgkmcnt(8)
	v_mfma_f32_32x32x16_bf16 v[218:233], v[140:143], v[104:107], v[218:233]
	ds_read_b64_tr_b16 v[140:141], v0 offset:18432
	ds_read_b64_tr_b16 v[142:143], v0 offset:18944
	v_add_f32_e32 v250, v246, v247
	v_cmp_ngt_f32_e32 vcc, 0x43800000, v250
	s_cbranch_vccnz .Lmla_l0_fbA
	v_add_f32_e32 v200, v200, v250
	v_cvt_pk_bf16_f32 v64, v64, v65
	v_cvt_pk_bf16_f32 v65, v66, v67
	s_waitcnt lgkmcnt(9)
	v_mfma_f32_32x32x16_bf16 v[218:233], v[234:237], v[116:119], v[218:233]
	ds_read_b64_tr_b16 v[234:235], v0 offset:15360
	ds_read_b64_tr_b16 v[236:237], v0 offset:15872
	v_cvt_pk_bf16_f32 v66, v68, v69
	v_cvt_pk_bf16_f32 v67, v70, v71
	v_cvt_pk_bf16_f32 v68, v72, v73
	v_cvt_pk_bf16_f32 v69, v74, v75
	v_cvt_pk_bf16_f32 v70, v76, v77
	s_waitcnt lgkmcnt(10)
	v_mfma_f32_32x32x16_bf16 v[218:233], v[240:243], v[120:123], v[218:233]
	ds_read_b64_tr_b16 v[240:241], v0 offset:19456
	ds_read_b64_tr_b16 v[242:243], v0 offset:19968
	v_cvt_pk_bf16_f32 v71, v78, v79
	v_cvt_pk_bf16_f32 v48, v48, v49
	v_cvt_pk_bf16_f32 v49, v50, v51
	v_cvt_pk_bf16_f32 v50, v52, v53
	v_cvt_pk_bf16_f32 v51, v54, v55
	v_cvt_pk_bf16_f32 v52, v56, v57
	v_cvt_pk_bf16_f32 v53, v58, v59
	v_cvt_pk_bf16_f32 v54, v60, v61
	v_cvt_pk_bf16_f32 v55, v62, v63
	v_exp_f32_e32 v202, v202
	v_exp_f32_e32 v203, v203
	s_waitcnt lgkmcnt(10)
	v_mfma_f32_32x32x16_bf16 v[32:47], v[2:5], v[64:67], v[32:47]
	v_exp_f32_e32 v204, v204
	v_exp_f32_e32 v205, v205
	v_exp_f32_e32 v206, v206
	v_exp_f32_e32 v207, v207
	v_exp_f32_e32 v208, v208
	s_waitcnt lgkmcnt(8)
	v_mfma_f32_32x32x16_bf16 v[16:31], v[6:9], v[64:67], v[16:31]
	v_exp_f32_e32 v209, v209
	v_pk_add_f32 v[246:247], v[202:203], v[204:205]
	v_exp_f32_e32 v210, v210
	v_exp_f32_e32 v211, v211
	v_exp_f32_e32 v212, v212
	s_waitcnt lgkmcnt(6)
	v_mfma_f32_32x32x16_bf16 v[32:47], v[10:13], v[68:71], v[32:47]
	ds_read_b64_tr_b16 v[2:3], v0 offset:16384
	ds_read_b64_tr_b16 v[4:5], v0 offset:16896
	v_exp_f32_e32 v213, v213
	v_pk_add_f32 v[248:249], v[206:207], v[208:209]
	v_exp_f32_e32 v214, v214
	v_exp_f32_e32 v215, v215
	v_pk_add_f32 v[246:247], v[246:247], v[210:211]
	s_waitcnt lgkmcnt(6)
	v_mfma_f32_32x32x16_bf16 v[16:31], v[140:143], v[68:71], v[16:31]
	ds_read_b64_tr_b16 v[6:7], v0 offset:20480
	ds_read_b64_tr_b16 v[8:9], v0 offset:20992
	v_exp_f32_e32 v216, v216
	v_exp_f32_e32 v217, v217
	v_pk_add_f32 v[248:249], v[248:249], v[212:213]
	v_exp_f32_e32 v218, v218
	v_exp_f32_e32 v219, v219
	s_waitcnt lgkmcnt(6)
	v_mfma_f32_32x32x16_bf16 v[32:47], v[234:237], v[48:51], v[32:47]
	ds_read_b64_tr_b16 v[72:73], v0 offset:34816
	ds_read_b64_tr_b16 v[74:75], v0 offset:35328
	v_pk_add_f32 v[246:247], v[246:247], v[214:215]
	v_exp_f32_e32 v220, v220
	v_exp_f32_e32 v221, v221
	v_pk_add_f32 v[248:249], v[248:249], v[216:217]
	v_exp_f32_e32 v222, v222
	s_waitcnt lgkmcnt(6)
	v_mfma_f32_32x32x16_bf16 v[16:31], v[240:243], v[48:51], v[16:31]
	ds_read_b64_tr_b16 v[76:77], v0 offset:38912
	ds_read_b64_tr_b16 v[78:79], v0 offset:39424
	v_exp_f32_e32 v223, v223
	v_pk_add_f32 v[246:247], v[246:247], v[218:219]
	v_exp_f32_e32 v224, v224
	v_exp_f32_e32 v225, v225
	v_pk_add_f32 v[248:249], v[248:249], v[220:221]
	s_waitcnt lgkmcnt(6)
	v_mfma_f32_32x32x16_bf16 v[32:47], v[2:5], v[52:55], v[32:47]
	ds_read_b64_tr_b16 v[56:57], v0 offset:35840
	ds_read_b64_tr_b16 v[58:59], v0 offset:36352
	v_exp_f32_e32 v226, v226
	v_exp_f32_e32 v227, v227
	v_pk_add_f32 v[246:247], v[246:247], v[222:223]
	v_exp_f32_e32 v228, v228
	v_exp_f32_e32 v229, v229
	s_waitcnt lgkmcnt(6)
	v_mfma_f32_32x32x16_bf16 v[16:31], v[6:9], v[52:55], v[16:31]
	ds_read_b64_tr_b16 v[60:61], v0 offset:39936
	ds_read_b64_tr_b16 v[62:63], v0 offset:40448
	v_pk_add_f32 v[248:249], v[248:249], v[224:225]
	v_exp_f32_e32 v230, v230
	v_exp_f32_e32 v231, v231
	v_pk_add_f32 v[246:247], v[246:247], v[226:227]
	v_exp_f32_e32 v232, v232
	v_exp_f32_e32 v233, v233
	v_pk_add_f32 v[248:249], v[248:249], v[228:229]
	v_pk_add_f32 v[246:247], v[246:247], v[230:231]
	v_pk_add_f32 v[248:249], v[248:249], v[232:233]
	v_pk_add_f32 v[246:247], v[246:247], v[248:249]
	v_add_f32_e32 v250, v246, v247
	v_cmp_ngt_f32_e32 vcc, 0x43800000, v250
	s_cbranch_vccnz .Lmla_l0_fbB
	v_add_f32_e32 v200, v200, v250
	v_cvt_pk_bf16_f32 v202, v202, v203
	v_cvt_pk_bf16_f32 v203, v204, v205
	v_cvt_pk_bf16_f32 v204, v206, v207
	v_cvt_pk_bf16_f32 v205, v208, v209
	v_cvt_pk_bf16_f32 v206, v210, v211
	v_cvt_pk_bf16_f32 v207, v212, v213
	v_cvt_pk_bf16_f32 v208, v214, v215
	v_cvt_pk_bf16_f32 v209, v216, v217
	v_cvt_pk_bf16_f32 v218, v218, v219
	v_cvt_pk_bf16_f32 v219, v220, v221
	v_cvt_pk_bf16_f32 v220, v222, v223
	v_cvt_pk_bf16_f32 v221, v224, v225
	v_cvt_pk_bf16_f32 v222, v226, v227
	v_cvt_pk_bf16_f32 v223, v228, v229
	v_cvt_pk_bf16_f32 v224, v230, v231
	v_cvt_pk_bf16_f32 v225, v232, v233
	s_waitcnt lgkmcnt(6)
	v_mfma_f32_32x32x16_bf16 v[32:47], v[72:75], v[202:205], v[32:47]
	ds_read_b64_tr_b16 v[10:11], v0 offset:36864
	ds_read_b64_tr_b16 v[12:13], v0 offset:37376
	s_waitcnt vmcnt(0)
	s_xor_b32 s16, s18, 1
	s_mul_i32 s16, s16, 0xa800
	v_add_u32_e32 v254, s16, v170
	s_mov_b64 exec, s[2:3]
	v_add_u32_e32 v254, v254, v149
	v_add3_u32 v254, v254, v171, v169
	v_add_u32_e32 v254, 0x1c00, v254
	s_not_b64 exec, exec
	v_add3_u32 v254, v254, v192, v193
	s_mov_b64 exec, -1
	ds_write_b128 v254, v[80:83]
	v_add_u32_e32 v254, s16, v172
	s_mov_b64 exec, s[4:5]
	v_add_u32_e32 v254, v254, v149
	v_add3_u32 v254, v254, v173, v169
	v_add_u32_e32 v254, 0x1c00, v254
	s_not_b64 exec, exec
	v_add3_u32 v254, v254, v194, v195
	s_mov_b64 exec, -1
	ds_write_b128 v254, v[84:87]
	v_add_u32_e32 v254, s16, v174
	s_mov_b64 exec, s[6:7]
	v_add_u32_e32 v254, v254, v149
	v_add3_u32 v254, v254, v175, v169
	v_add_u32_e32 v254, 0x1c00, v254
	s_not_b64 exec, exec
	v_add3_u32 v254, v254, v196, v197
	s_mov_b64 exec, -1
	ds_write_b128 v254, v[88:91]
	v_add_u32_e32 v254, s16, v176
	s_mov_b64 exec, s[8:9]
	v_add_u32_e32 v254, v254, v149
	v_add3_u32 v254, v254, v177, v169
	v_add_u32_e32 v254, 0x1c00, v254
	s_not_b64 exec, exec
	v_add3_u32 v254, v254, v198, v199
	s_mov_b64 exec, -1
	ds_write_b128 v254, v[108:111]
	v_add_u32_e32 v254, s16, v178
	s_mov_b64 exec, s[10:11]
	v_add_u32_e32 v254, v254, v149
	v_add3_u32 v254, v254, v179, v169
	v_add_u32_e32 v254, 0x1c00, v254
	s_not_b64 exec, exec
	v_add3_u32 v254, v254, v180, v181
	s_mov_b64 exec, -1
	ds_write_b128 v254, v[112:115]
	s_waitcnt lgkmcnt(11)
	v_mfma_f32_32x32x16_bf16 v[16:31], v[76:79], v[202:205], v[16:31]
	ds_read_b64_tr_b16 v[140:141], v0 offset:40960
	ds_read_b64_tr_b16 v[142:143], v0 offset:41472
	s_waitcnt lgkmcnt(11)
	v_mfma_f32_32x32x16_bf16 v[32:47], v[56:59], v[206:209], v[32:47]
	ds_read_b64_tr_b16 v[234:235], v0 offset:37888
	ds_read_b64_tr_b16 v[236:237], v0 offset:38400
	s_waitcnt lgkmcnt(11)
	v_mfma_f32_32x32x16_bf16 v[16:31], v[60:63], v[206:209], v[16:31]
	ds_read_b64_tr_b16 v[240:241], v0 offset:41984
	ds_read_b64_tr_b16 v[242:243], v0 offset:42496
	s_waitcnt lgkmcnt(11)
	v_mfma_f32_32x32x16_bf16 v[32:47], v[10:13], v[218:221], v[32:47]
	s_waitcnt lgkmcnt(4)
	v_mfma_f32_32x32x16_bf16 v[16:31], v[140:143], v[218:221], v[16:31]
	s_add_i32 s0, s19, 0xc0
	s_cmp_le_i32 s0, s67
	s_cbranch_scc0 .Lmla_l0_noload
	s_add_u32 s16, s12, 0x30000
	s_addc_u32 s17, s13, 0
	s_add_i32 s0, s76, 1
	s_lshl_b32 s0, s0, 1
	v_mov_b32_e32 v255, 0
	s_mov_b64 exec, s[2:3]
	v_or_b32_e32 v254, s0, v186
	v_lshl_add_u32 v254, v254, 6, v164
	v_lshlrev_b64 v[252:253], 10, v[254:255]
	v_lshl_add_u64 v[252:253], v[144:145], 0, v[252:253]
	s_not_b64 exec, exec
	v_lshl_add_u64 v[252:253], v[158:159], 0, s[16:17]
	s_mov_b64 exec, -1
	global_load_dwordx4 v[80:83], v[252:253], off
	s_mov_b64 exec, s[4:5]
	v_or_b32_e32 v254, s0, v187
	v_lshl_add_u32 v254, v254, 6, v165
	v_lshlrev_b64 v[252:253], 10, v[254:255]
	v_lshl_add_u64 v[252:253], v[144:145], 0, v[252:253]
	s_not_b64 exec, exec
	v_lshl_add_u64 v[252:253], v[156:157], 0, s[16:17]
	s_mov_b64 exec, -1
	global_load_dwordx4 v[84:87], v[252:253], off
	s_mov_b64 exec, s[6:7]
	v_or_b32_e32 v254, s0, v188
	v_lshl_add_u32 v254, v254, 6, v166
	v_lshlrev_b64 v[252:253], 10, v[254:255]
	v_lshl_add_u64 v[252:253], v[144:145], 0, v[252:253]
	s_not_b64 exec, exec
	v_lshl_add_u64 v[252:253], v[154:155], 0, s[16:17]
	s_mov_b64 exec, -1
	global_load_dwordx4 v[88:91], v[252:253], off
	s_mov_b64 exec, s[8:9]
	v_or_b32_e32 v254, s0, v189
	v_lshl_add_u32 v254, v254, 6, v167
	v_lshlrev_b64 v[252:253], 10, v[254:255]
	v_lshl_add_u64 v[252:253], v[144:145], 0, v[252:253]
	s_not_b64 exec, exec
	v_lshl_add_u64 v[252:253], v[152:153], 0, s[16:17]
	s_mov_b64 exec, -1
	global_load_dwordx4 v[108:111], v[252:253], off
	s_mov_b64 exec, s[10:11]
	v_or_b32_e32 v254, s0, v190
	v_lshl_add_u32 v254, v254, 6, v168
	v_lshlrev_b64 v[252:253], 10, v[254:255]
	v_lshl_add_u64 v[252:253], v[144:145], 0, v[252:253]
	s_not_b64 exec, exec
	v_lshl_add_u64 v[252:253], v[150:151], 0, s[16:17]
	s_mov_b64 exec, -1
	global_load_dwordx4 v[112:115], v[252:253], off
.Lmla_l0_noload:
	s_waitcnt lgkmcnt(2)
	v_mfma_f32_32x32x16_bf16 v[32:47], v[234:237], v[222:225], v[32:47]
	s_waitcnt lgkmcnt(0)
	v_mfma_f32_32x32x16_bf16 v[16:31], v[240:243], v[222:225], v[16:31]
	s_xor_b32 s18, s18, 1
	s_addk_i32 s19, 0x80
	s_add_u32 s12, s12, 0x30000
	s_addc_u32 s13, s13, 0
	s_add_i32 s61, s61, 1
	s_waitcnt lgkmcnt(0)
	s_barrier
	s_add_i32 s0, s19, 64
	s_cmp_le_i32 s0, s67
	s_cbranch_scc0 .LBB0_594
	s_add_i32 s76, s76, 1
	s_branch .Lmla_fast_l0

.Lmla_l1_negm_ok:
	s_nop 1
	s_waitcnt lgkmcnt(11)
	v_mfma_f32_32x32x16_bf16 v[64:79], v[2:5], v[92:95], v[124:139]
	ds_read_b128 v[2:5], v14 offset:21504
	s_waitcnt lgkmcnt(11)
	v_mfma_f32_32x32x16_bf16 v[64:79], v[6:9], v[96:99], v[64:79]
	ds_read_b128 v[6:9], v14 offset:21536
	s_waitcnt lgkmcnt(11)
	v_mfma_f32_32x32x16_bf16 v[64:79], v[10:13], v[100:103], v[64:79]
	ds_read_b128 v[10:13], v14 offset:21568
	s_waitcnt lgkmcnt(11)
	v_mfma_f32_32x32x16_bf16 v[64:79], v[140:143], v[104:107], v[64:79]
	ds_read_b128 v[140:143], v14 offset:21600
	s_waitcnt lgkmcnt(11)
	v_mfma_f32_32x32x16_bf16 v[64:79], v[234:237], v[116:119], v[64:79]
	ds_read_b128 v[234:237], v14 offset:21632
	s_waitcnt lgkmcnt(11)
	v_mfma_f32_32x32x16_bf16 v[64:79], v[240:243], v[120:123], v[64:79]
	ds_read_b128 v[240:243], v14 offset:21664
	s_waitcnt lgkmcnt(11)
	v_mfma_f32_32x32x16_bf16 v[48:63], v[202:205], v[92:95], v[124:139]
	s_waitcnt lgkmcnt(10)
	v_mfma_f32_32x32x16_bf16 v[48:63], v[206:209], v[96:99], v[48:63]
	s_waitcnt lgkmcnt(9)
	v_mfma_f32_32x32x16_bf16 v[48:63], v[210:213], v[100:103], v[48:63]
	s_waitcnt lgkmcnt(8)
	v_mfma_f32_32x32x16_bf16 v[48:63], v[214:217], v[104:107], v[48:63]
	s_waitcnt lgkmcnt(7)
	v_mfma_f32_32x32x16_bf16 v[48:63], v[218:221], v[116:119], v[48:63]
	s_waitcnt lgkmcnt(6)
	v_mfma_f32_32x32x16_bf16 v[48:63], v[222:225], v[120:123], v[48:63]
	v_exp_f32_e32 v64, v64
	v_exp_f32_e32 v65, v65
	s_waitcnt lgkmcnt(5)
	v_mfma_f32_32x32x16_bf16 v[202:217], v[2:5], v[92:95], v[124:139]
	ds_read_b128 v[2:5], v14 offset:28160
	v_exp_f32_e32 v66, v66
	v_exp_f32_e32 v67, v67
	v_exp_f32_e32 v68, v68
	v_exp_f32_e32 v69, v69
	v_exp_f32_e32 v70, v70
	s_waitcnt lgkmcnt(5)
	v_mfma_f32_32x32x16_bf16 v[202:217], v[6:9], v[96:99], v[202:217]
	ds_read_b128 v[6:9], v14 offset:28192
	v_exp_f32_e32 v71, v71
	v_pk_add_f32 v[246:247], v[64:65], v[66:67]
	v_exp_f32_e32 v72, v72
	v_exp_f32_e32 v73, v73
	v_exp_f32_e32 v74, v74
	s_waitcnt lgkmcnt(5)
	v_mfma_f32_32x32x16_bf16 v[202:217], v[10:13], v[100:103], v[202:217]
	ds_read_b128 v[10:13], v14 offset:28224
	v_exp_f32_e32 v75, v75
	v_pk_add_f32 v[248:249], v[68:69], v[70:71]
	v_exp_f32_e32 v76, v76
	v_exp_f32_e32 v77, v77
	v_pk_add_f32 v[246:247], v[246:247], v[72:73]
	s_waitcnt lgkmcnt(5)
	v_mfma_f32_32x32x16_bf16 v[202:217], v[140:143], v[104:107], v[202:217]
	ds_read_b128 v[140:143], v14 offset:28256
	v_exp_f32_e32 v78, v78
	v_exp_f32_e32 v79, v79
	v_pk_add_f32 v[248:249], v[248:249], v[74:75]
	v_exp_f32_e32 v48, v48
	v_exp_f32_e32 v49, v49
	s_waitcnt lgkmcnt(5)
	v_mfma_f32_32x32x16_bf16 v[202:217], v[234:237], v[116:119], v[202:217]
	ds_read_b128 v[234:237], v14 offset:28288
	v_pk_add_f32 v[246:247], v[246:247], v[76:77]
	v_exp_f32_e32 v50, v50
	v_exp_f32_e32 v51, v51
	v_pk_add_f32 v[248:249], v[248:249], v[78:79]
	v_exp_f32_e32 v52, v52
	s_waitcnt lgkmcnt(5)
	v_mfma_f32_32x32x16_bf16 v[202:217], v[240:243], v[120:123], v[202:217]
	ds_read_b128 v[240:243], v14 offset:28320
	v_exp_f32_e32 v53, v53
	v_pk_add_f32 v[246:247], v[246:247], v[48:49]
	v_exp_f32_e32 v54, v54
	v_exp_f32_e32 v55, v55
	v_pk_add_f32 v[248:249], v[248:249], v[50:51]
	s_waitcnt lgkmcnt(5)
	v_mfma_f32_32x32x16_bf16 v[218:233], v[2:5], v[92:95], v[124:139]
	ds_read_b64_tr_b16 v[2:3], v0 offset:13312
	ds_read_b64_tr_b16 v[4:5], v0 offset:13824
	v_exp_f32_e32 v56, v56
	v_exp_f32_e32 v57, v57
	v_pk_add_f32 v[246:247], v[246:247], v[52:53]
	v_exp_f32_e32 v58, v58
	v_exp_f32_e32 v59, v59
	s_waitcnt lgkmcnt(6)
	v_mfma_f32_32x32x16_bf16 v[218:233], v[6:9], v[96:99], v[218:233]
	ds_read_b64_tr_b16 v[6:7], v0 offset:17408
	ds_read_b64_tr_b16 v[8:9], v0 offset:17920
	v_pk_add_f32 v[248:249], v[248:249], v[54:55]
	v_exp_f32_e32 v60, v60
	v_exp_f32_e32 v61, v61
	v_pk_add_f32 v[246:247], v[246:247], v[56:57]
	v_exp_f32_e32 v62, v62
	s_waitcnt lgkmcnt(7)
	v_mfma_f32_32x32x16_bf16 v[218:233], v[10:13], v[100:103], v[218:233]
	ds_read_b64_tr_b16 v[10:11], v0 offset:14336
	ds_read_b64_tr_b16 v[12:13], v0 offset:14848
	v_exp_f32_e32 v63, v63
	v_pk_add_f32 v[248:249], v[248:249], v[58:59]
	v_pk_add_f32 v[246:247], v[246:247], v[60:61]
	v_pk_add_f32 v[248:249], v[248:249], v[62:63]
	v_pk_add_f32 v[246:247], v[246:247], v[248:249]
	s_waitcnt lgkmcnt(8)
	v_mfma_f32_32x32x16_bf16 v[218:233], v[140:143], v[104:107], v[218:233]
	ds_read_b64_tr_b16 v[140:141], v0 offset:18432
	ds_read_b64_tr_b16 v[142:143], v0 offset:18944
	v_add_f32_e32 v250, v246, v247
	v_cmp_ngt_f32_e32 vcc, 0x43800000, v250
	s_cbranch_vccnz .Lmla_l1_fbA
	v_add_f32_e32 v200, v200, v250
	v_cvt_pk_bf16_f32 v64, v64, v65
	v_cvt_pk_bf16_f32 v65, v66, v67
	s_waitcnt lgkmcnt(9)
	v_mfma_f32_32x32x16_bf16 v[218:233], v[234:237], v[116:119], v[218:233]
	ds_read_b64_tr_b16 v[234:235], v0 offset:15360
	ds_read_b64_tr_b16 v[236:237], v0 offset:15872
	v_cvt_pk_bf16_f32 v66, v68, v69
	v_cvt_pk_bf16_f32 v67, v70, v71
	v_cvt_pk_bf16_f32 v68, v72, v73
	v_cvt_pk_bf16_f32 v69, v74, v75
	v_cvt_pk_bf16_f32 v70, v76, v77
	s_waitcnt lgkmcnt(10)
	v_mfma_f32_32x32x16_bf16 v[218:233], v[240:243], v[120:123], v[218:233]
	ds_read_b64_tr_b16 v[240:241], v0 offset:19456
	ds_read_b64_tr_b16 v[242:243], v0 offset:19968
	v_cvt_pk_bf16_f32 v71, v78, v79
	v_cvt_pk_bf16_f32 v48, v48, v49
	v_cvt_pk_bf16_f32 v49, v50, v51
	v_cvt_pk_bf16_f32 v50, v52, v53
	v_cvt_pk_bf16_f32 v51, v54, v55
	v_cvt_pk_bf16_f32 v52, v56, v57
	v_cvt_pk_bf16_f32 v53, v58, v59
	v_cvt_pk_bf16_f32 v54, v60, v61
	v_cvt_pk_bf16_f32 v55, v62, v63
	v_exp_f32_e32 v202, v202
	v_exp_f32_e32 v203, v203
	s_waitcnt lgkmcnt(10)
	v_mfma_f32_32x32x16_bf16 v[32:47], v[2:5], v[64:67], v[32:47]
	v_exp_f32_e32 v204, v204
	v_exp_f32_e32 v205, v205
	v_exp_f32_e32 v206, v206
	v_exp_f32_e32 v207, v207
	v_exp_f32_e32 v208, v208
	s_waitcnt lgkmcnt(8)
	v_mfma_f32_32x32x16_bf16 v[16:31], v[6:9], v[64:67], v[16:31]
	v_exp_f32_e32 v209, v209
	v_pk_add_f32 v[246:247], v[202:203], v[204:205]
	v_exp_f32_e32 v210, v210
	v_exp_f32_e32 v211, v211
	v_exp_f32_e32 v212, v212
	s_waitcnt lgkmcnt(6)
	v_mfma_f32_32x32x16_bf16 v[32:47], v[10:13], v[68:71], v[32:47]
	ds_read_b64_tr_b16 v[2:3], v0 offset:16384
	ds_read_b64_tr_b16 v[4:5], v0 offset:16896
	v_exp_f32_e32 v213, v213
	v_pk_add_f32 v[248:249], v[206:207], v[208:209]
	v_exp_f32_e32 v214, v214
	v_exp_f32_e32 v215, v215
	v_pk_add_f32 v[246:247], v[246:247], v[210:211]
	s_waitcnt lgkmcnt(6)
	v_mfma_f32_32x32x16_bf16 v[16:31], v[140:143], v[68:71], v[16:31]
	ds_read_b64_tr_b16 v[6:7], v0 offset:20480
	ds_read_b64_tr_b16 v[8:9], v0 offset:20992
	v_exp_f32_e32 v216, v216
	v_exp_f32_e32 v217, v217
	v_pk_add_f32 v[248:249], v[248:249], v[212:213]
	v_exp_f32_e32 v218, v218
	v_exp_f32_e32 v219, v219
	s_waitcnt lgkmcnt(6)
	v_mfma_f32_32x32x16_bf16 v[32:47], v[234:237], v[48:51], v[32:47]
	ds_read_b64_tr_b16 v[72:73], v0 offset:34816
	ds_read_b64_tr_b16 v[74:75], v0 offset:35328
	v_pk_add_f32 v[246:247], v[246:247], v[214:215]
	v_exp_f32_e32 v220, v220
	v_exp_f32_e32 v221, v221
	v_pk_add_f32 v[248:249], v[248:249], v[216:217]
	v_exp_f32_e32 v222, v222
	s_waitcnt lgkmcnt(6)
	v_mfma_f32_32x32x16_bf16 v[16:31], v[240:243], v[48:51], v[16:31]
	ds_read_b64_tr_b16 v[76:77], v0 offset:38912
	ds_read_b64_tr_b16 v[78:79], v0 offset:39424
	v_exp_f32_e32 v223, v223
	v_pk_add_f32 v[246:247], v[246:247], v[218:219]
	v_exp_f32_e32 v224, v224
	v_exp_f32_e32 v225, v225
	v_pk_add_f32 v[248:249], v[248:249], v[220:221]
	s_waitcnt lgkmcnt(6)
	v_mfma_f32_32x32x16_bf16 v[32:47], v[2:5], v[52:55], v[32:47]
	ds_read_b64_tr_b16 v[56:57], v0 offset:35840
	ds_read_b64_tr_b16 v[58:59], v0 offset:36352
	v_exp_f32_e32 v226, v226
	v_exp_f32_e32 v227, v227
	v_pk_add_f32 v[246:247], v[246:247], v[222:223]
	v_exp_f32_e32 v228, v228
	v_exp_f32_e32 v229, v229
	s_waitcnt lgkmcnt(6)
	v_mfma_f32_32x32x16_bf16 v[16:31], v[6:9], v[52:55], v[16:31]
	ds_read_b64_tr_b16 v[60:61], v0 offset:39936
	ds_read_b64_tr_b16 v[62:63], v0 offset:40448
	v_pk_add_f32 v[248:249], v[248:249], v[224:225]
	v_exp_f32_e32 v230, v230
	v_exp_f32_e32 v231, v231
	v_pk_add_f32 v[246:247], v[246:247], v[226:227]
	v_exp_f32_e32 v232, v232
	v_exp_f32_e32 v233, v233
	v_pk_add_f32 v[248:249], v[248:249], v[228:229]
	v_pk_add_f32 v[246:247], v[246:247], v[230:231]
	v_pk_add_f32 v[248:249], v[248:249], v[232:233]
	v_pk_add_f32 v[246:247], v[246:247], v[248:249]
	v_add_f32_e32 v250, v246, v247
	v_cmp_ngt_f32_e32 vcc, 0x43800000, v250
	s_cbranch_vccnz .Lmla_l1_fbB
	v_add_f32_e32 v200, v200, v250
	v_cvt_pk_bf16_f32 v202, v202, v203
	v_cvt_pk_bf16_f32 v203, v204, v205
	v_cvt_pk_bf16_f32 v204, v206, v207
	v_cvt_pk_bf16_f32 v205, v208, v209
	v_cvt_pk_bf16_f32 v206, v210, v211
	v_cvt_pk_bf16_f32 v207, v212, v213
	v_cvt_pk_bf16_f32 v208, v214, v215
	v_cvt_pk_bf16_f32 v209, v216, v217
	v_cvt_pk_bf16_f32 v218, v218, v219
	v_cvt_pk_bf16_f32 v219, v220, v221
	v_cvt_pk_bf16_f32 v220, v222, v223
	v_cvt_pk_bf16_f32 v221, v224, v225
	v_cvt_pk_bf16_f32 v222, v226, v227
	v_cvt_pk_bf16_f32 v223, v228, v229
	v_cvt_pk_bf16_f32 v224, v230, v231
	v_cvt_pk_bf16_f32 v225, v232, v233
	s_waitcnt lgkmcnt(6)
	v_mfma_f32_32x32x16_bf16 v[32:47], v[72:75], v[202:205], v[32:47]
	ds_read_b64_tr_b16 v[10:11], v0 offset:36864
	ds_read_b64_tr_b16 v[12:13], v0 offset:37376
	s_waitcnt vmcnt(0)
	s_xor_b32 s16, s18, 1
	s_mul_i32 s16, s16, 0xa800
	v_add_u32_e32 v254, s16, v170
	s_mov_b64 exec, s[2:3]
	v_add_u32_e32 v254, v254, v149
	v_add3_u32 v254, v254, v171, v169
	v_add_u32_e32 v254, 0x1c00, v254
	s_not_b64 exec, exec
	v_add3_u32 v254, v254, v192, v193
	s_mov_b64 exec, -1
	ds_write_b128 v254, v[80:83]
	v_add_u32_e32 v254, s16, v172
	s_mov_b64 exec, s[4:5]
	v_add_u32_e32 v254, v254, v149
	v_add3_u32 v254, v254, v173, v169
	v_add_u32_e32 v254, 0x1c00, v254
	s_not_b64 exec, exec
	v_add3_u32 v254, v254, v194, v195
	s_mov_b64 exec, -1
	ds_write_b128 v254, v[84:87]
	v_add_u32_e32 v254, s16, v174
	s_mov_b64 exec, s[6:7]
	v_add_u32_e32 v254, v254, v149
	v_add3_u32 v254, v254, v175, v169
	v_add_u32_e32 v254, 0x1c00, v254
	s_not_b64 exec, exec
	v_add3_u32 v254, v254, v196, v197
	s_mov_b64 exec, -1
	ds_write_b128 v254, v[88:91]
	v_add_u32_e32 v254, s16, v176
	s_mov_b64 exec, s[8:9]
	v_add_u32_e32 v254, v254, v149
	v_add3_u32 v254, v254, v177, v169
	v_add_u32_e32 v254, 0x1c00, v254
	s_not_b64 exec, exec
	v_add3_u32 v254, v254, v198, v199
	s_mov_b64 exec, -1
	ds_write_b128 v254, v[108:111]
	v_add_u32_e32 v254, s16, v178
	s_mov_b64 exec, s[10:11]
	v_add_u32_e32 v254, v254, v149
	v_add3_u32 v254, v254, v179, v169
	v_add_u32_e32 v254, 0x1c00, v254
	s_not_b64 exec, exec
	v_add3_u32 v254, v254, v180, v181
	s_mov_b64 exec, -1
	ds_write_b128 v254, v[112:115]
	s_waitcnt lgkmcnt(11)
	v_mfma_f32_32x32x16_bf16 v[16:31], v[76:79], v[202:205], v[16:31]
	ds_read_b64_tr_b16 v[140:141], v0 offset:40960
	ds_read_b64_tr_b16 v[142:143], v0 offset:41472
	s_waitcnt lgkmcnt(11)
	v_mfma_f32_32x32x16_bf16 v[32:47], v[56:59], v[206:209], v[32:47]
	ds_read_b64_tr_b16 v[234:235], v0 offset:37888
	ds_read_b64_tr_b16 v[236:237], v0 offset:38400
	s_waitcnt lgkmcnt(11)
	v_mfma_f32_32x32x16_bf16 v[16:31], v[60:63], v[206:209], v[16:31]
	ds_read_b64_tr_b16 v[240:241], v0 offset:41984
	ds_read_b64_tr_b16 v[242:243], v0 offset:42496
	s_waitcnt lgkmcnt(11)
	v_mfma_f32_32x32x16_bf16 v[32:47], v[10:13], v[218:221], v[32:47]
	s_waitcnt lgkmcnt(4)
	v_mfma_f32_32x32x16_bf16 v[16:31], v[140:143], v[218:221], v[16:31]
	s_add_i32 s0, s19, 0xc0
	s_cmp_le_i32 s0, s84
	s_cbranch_scc0 .Lmla_l1_noload
	s_add_u32 s16, s12, 0x30000
	s_addc_u32 s17, s13, 0
	s_add_i32 s0, s94, 1
	s_lshl_b32 s0, s0, 1
	v_mov_b32_e32 v255, 0
	s_mov_b64 exec, s[2:3]
	v_or_b32_e32 v254, s0, v186
	v_lshl_add_u32 v254, v254, 6, v164
	v_lshlrev_b64 v[252:253], 10, v[254:255]
	v_lshl_add_u64 v[252:253], v[144:145], 0, v[252:253]
	s_not_b64 exec, exec
	v_lshl_add_u64 v[252:253], v[158:159], 0, s[16:17]
	s_mov_b64 exec, -1
	global_load_dwordx4 v[80:83], v[252:253], off
	s_mov_b64 exec, s[4:5]
	v_or_b32_e32 v254, s0, v187
	v_lshl_add_u32 v254, v254, 6, v165
	v_lshlrev_b64 v[252:253], 10, v[254:255]
	v_lshl_add_u64 v[252:253], v[144:145], 0, v[252:253]
	s_not_b64 exec, exec
	v_lshl_add_u64 v[252:253], v[156:157], 0, s[16:17]
	s_mov_b64 exec, -1
	global_load_dwordx4 v[84:87], v[252:253], off
	s_mov_b64 exec, s[6:7]
	v_or_b32_e32 v254, s0, v188
	v_lshl_add_u32 v254, v254, 6, v166
	v_lshlrev_b64 v[252:253], 10, v[254:255]
	v_lshl_add_u64 v[252:253], v[144:145], 0, v[252:253]
	s_not_b64 exec, exec
	v_lshl_add_u64 v[252:253], v[154:155], 0, s[16:17]
	s_mov_b64 exec, -1
	global_load_dwordx4 v[88:91], v[252:253], off
	s_mov_b64 exec, s[8:9]
	v_or_b32_e32 v254, s0, v189
	v_lshl_add_u32 v254, v254, 6, v167
	v_lshlrev_b64 v[252:253], 10, v[254:255]
	v_lshl_add_u64 v[252:253], v[144:145], 0, v[252:253]
	s_not_b64 exec, exec
	v_lshl_add_u64 v[252:253], v[152:153], 0, s[16:17]
	s_mov_b64 exec, -1
	global_load_dwordx4 v[108:111], v[252:253], off
	s_mov_b64 exec, s[10:11]
	v_or_b32_e32 v254, s0, v190
	v_lshl_add_u32 v254, v254, 6, v168
	v_lshlrev_b64 v[252:253], 10, v[254:255]
	v_lshl_add_u64 v[252:253], v[144:145], 0, v[252:253]
	s_not_b64 exec, exec
	v_lshl_add_u64 v[252:253], v[150:151], 0, s[16:17]
	s_mov_b64 exec, -1
	global_load_dwordx4 v[112:115], v[252:253], off
.Lmla_l1_noload:
	s_waitcnt lgkmcnt(2)
	v_mfma_f32_32x32x16_bf16 v[32:47], v[234:237], v[222:225], v[32:47]
	s_waitcnt lgkmcnt(0)
	v_mfma_f32_32x32x16_bf16 v[16:31], v[240:243], v[222:225], v[16:31]
	s_xor_b32 s18, s18, 1
	s_addk_i32 s19, 0x80
	s_add_u32 s12, s12, 0x30000
	s_addc_u32 s13, s13, 0
	s_add_i32 s63, s63, 1
	s_waitcnt lgkmcnt(0)
	s_barrier
	s_add_i32 s0, s19, 64
	s_cmp_le_i32 s0, s84
	s_cbranch_scc0 .LBB0_1884
	s_add_i32 s94, s94, 1
	s_branch .Lmla_fast_l1
